# PV V-fragment reads prefetched 4 deep with counted lgkmcnt waits (both local-mode copies)
# baseline (speedup 1.0000x reference)
; #define LAS __attribute__((address_space(3)))
; __device__ __forceinline__ s16x4 vtr(const LAS unsigned char* p) { return __builtin_bit_cast(s16x4, __builtin_amdgcn_ds_read_tr16_b64_v4i16((LAS s16x4*)p)); }
; template <bool MERGE> __device__ __forceinline__ void compute_b(LAS unsigned char* lds, const UD& x, unsigned char* ws, unsigned char* dout, int wid, int lane, const u32x4 (&pw)[10], float mx, float lsum) {
;     ...
;     f32x16 o[2]; o[0] = f32x16{}; o[1] = f32x16{};
;     const int vlane = ((lane >> 4) & 1) * 32 + (lane & 3) * 8 + (4 * hi + ((lane & 15) >> 2)) * 64;
; #pragma unroll
;     for (int g = 0; g < 10; ++g) {
;         const bf16x8 pa = __builtin_bit_cast(bf16x8, pw[g]);
; #pragma unroll
;         for (int d0 = 0; d0 < 2; ++d0) {
;             const LAS unsigned char* vp = lds + L_V + d0 * VDS + (sbase + 16 * g) * 64 + vlane;
;             const s16x4 lo = vtr(vp), hh = vtr(vp + 512);
;             const bf16x8 vf = (bf16x8){lo[0], lo[1], lo[2], lo[3], hh[0], hh[1], hh[2], hh[3]};
;             o[d0] = __builtin_amdgcn_mfma_f32_32x32x16_bf16(pa, vf, o[d0], 0, 0, 0);
;         }
;     }
;     LAS float* wsf = (LAS float*)(lds + L_WS + wid * 256);
;     LAS bf16_t* stg = (LAS bf16_t*)(lds + L_OST + wid * 4096);
;     if (hi == 0) {
;         wsf[r32] = lsum;
;         if (MERGE) wsf[32 + r32] = mx;
;         else { float* st = (float*)(ws + WS_STAT) + (((size_t)x.br * M + qtok) * NH + x.h) * 2; st[0] = mx; st[1] = lsum; }
.LBB0_689:
	v_lshl_add_u32 v71, s21, 6, v163
	v_add_u32_e32 v76, 0xe080, v71
	ds_read_b64_tr_b16 v[234:235], v71 offset:57472
	ds_read_b64_tr_b16 v[236:237], v71 offset:57984
	ds_read_b64_tr_b16 v[242:243], v76 offset:28736
	ds_read_b64_tr_b16 v[244:245], v76 offset:29248
	ds_read_b64_tr_b16 v[132:133], v71 offset:58496
	ds_read_b64_tr_b16 v[134:135], v71 offset:59008
	ds_read_b64_tr_b16 v[246:247], v76 offset:29760
	ds_read_b64_tr_b16 v[248:249], v76 offset:30272
	s_waitcnt lgkmcnt(6)
	v_mfma_f32_32x32x16_bf16 v[0:15], v[16:19], v[234:237], 0
	ds_read_b64_tr_b16 v[234:235], v71 offset:59520
	ds_read_b64_tr_b16 v[236:237], v71 offset:60032
	s_waitcnt lgkmcnt(6)
	v_mfma_f32_32x32x16_bf16 v[16:31], v[16:19], v[242:245], 0
	ds_read_b64_tr_b16 v[242:243], v76 offset:30784
	ds_read_b64_tr_b16 v[244:245], v76 offset:31296
	s_waitcnt lgkmcnt(6)
	v_mfma_f32_32x32x16_bf16 v[0:15], v[64:67], v[132:135], v[0:15]
	ds_read_b64_tr_b16 v[132:133], v71 offset:60544
	ds_read_b64_tr_b16 v[134:135], v71 offset:61056
	s_waitcnt lgkmcnt(6)
	v_mfma_f32_32x32x16_bf16 v[16:31], v[64:67], v[246:249], v[16:31]
	ds_read_b64_tr_b16 v[246:247], v76 offset:31808
	ds_read_b64_tr_b16 v[248:249], v76 offset:32320
	s_waitcnt lgkmcnt(6)
	v_mfma_f32_32x32x16_bf16 v[0:15], v[60:63], v[234:237], v[0:15]
	ds_read_b64_tr_b16 v[234:235], v71 offset:61568
	ds_read_b64_tr_b16 v[236:237], v71 offset:62080
	s_waitcnt lgkmcnt(6)
	v_mfma_f32_32x32x16_bf16 v[16:31], v[60:63], v[242:245], v[16:31]
	ds_read_b64_tr_b16 v[242:243], v76 offset:32832
	ds_read_b64_tr_b16 v[244:245], v76 offset:33344
	s_waitcnt lgkmcnt(6)
	v_mfma_f32_32x32x16_bf16 v[0:15], v[56:59], v[132:135], v[0:15]
	ds_read_b64_tr_b16 v[132:133], v71 offset:62592
	ds_read_b64_tr_b16 v[134:135], v71 offset:63104
	s_waitcnt lgkmcnt(6)
	v_mfma_f32_32x32x16_bf16 v[16:31], v[56:59], v[246:249], v[16:31]
	ds_read_b64_tr_b16 v[246:247], v76 offset:33856
	ds_read_b64_tr_b16 v[248:249], v76 offset:34368
	s_waitcnt lgkmcnt(6)
	v_mfma_f32_32x32x16_bf16 v[0:15], v[52:55], v[234:237], v[0:15]
	ds_read_b64_tr_b16 v[234:235], v71 offset:63616
	ds_read_b64_tr_b16 v[236:237], v71 offset:64128
	s_waitcnt lgkmcnt(6)
	v_mfma_f32_32x32x16_bf16 v[16:31], v[52:55], v[242:245], v[16:31]
	ds_read_b64_tr_b16 v[242:243], v76 offset:34880
	ds_read_b64_tr_b16 v[244:245], v76 offset:35392
	s_waitcnt lgkmcnt(6)
	v_mfma_f32_32x32x16_bf16 v[0:15], v[48:51], v[132:135], v[0:15]
	ds_read_b64_tr_b16 v[132:133], v71 offset:64640
	ds_read_b64_tr_b16 v[134:135], v71 offset:65152
	s_waitcnt lgkmcnt(6)
	v_mfma_f32_32x32x16_bf16 v[16:31], v[48:51], v[246:249], v[16:31]
	ds_read_b64_tr_b16 v[246:247], v76 offset:35904
	ds_read_b64_tr_b16 v[248:249], v76 offset:36416
	s_waitcnt lgkmcnt(6)
	v_mfma_f32_32x32x16_bf16 v[0:15], v[44:47], v[234:237], v[0:15]
	ds_read_b64_tr_b16 v[234:235], v76 offset:8192
	ds_read_b64_tr_b16 v[236:237], v76 offset:8704
	s_waitcnt lgkmcnt(6)
	v_mfma_f32_32x32x16_bf16 v[16:31], v[44:47], v[242:245], v[16:31]
	ds_read_b64_tr_b16 v[242:243], v76 offset:36928
	ds_read_b64_tr_b16 v[244:245], v76 offset:37440
	s_waitcnt lgkmcnt(6)
	v_mfma_f32_32x32x16_bf16 v[0:15], v[40:43], v[132:135], v[0:15]
	ds_read_b64_tr_b16 v[132:133], v76 offset:9216
	ds_read_b64_tr_b16 v[134:135], v76 offset:9728
	s_waitcnt lgkmcnt(6)
	v_mfma_f32_32x32x16_bf16 v[16:31], v[40:43], v[246:249], v[16:31]
	ds_read_b64_tr_b16 v[246:247], v76 offset:37952
	ds_read_b64_tr_b16 v[248:249], v76 offset:38464
	s_waitcnt lgkmcnt(6)
	v_mfma_f32_32x32x16_bf16 v[0:15], v[36:39], v[234:237], v[0:15]
	s_waitcnt lgkmcnt(4)
	v_mfma_f32_32x32x16_bf16 v[16:31], v[36:39], v[242:245], v[16:31]
	s_waitcnt lgkmcnt(2)
	v_mfma_f32_32x32x16_bf16 v[0:15], v[32:35], v[132:135], v[0:15]
	s_waitcnt lgkmcnt(0)
	v_mfma_f32_32x32x16_bf16 v[16:31], v[32:35], v[246:249], v[16:31]
	s_and_saveexec_b64 vcc, s[28:29]
	s_cbranch_execz .LBB0_633
	s_lshl_b32 s4, s13, 14
	s_add_i32 s80, s4, 0x4000
	s_ashr_i32 s4, s20, 31
	v_lshl_add_u64 v[32:33], v[152:153], 0, s[80:81]
	v_mov_b32_e32 v34, s20
	v_mov_b32_e32 v35, s4
	v_mad_u64_u32 v[34:35], s[4:5], v32, 12, v[34:35]
	v_mad_i32_i24 v35, v33, 12, v35
	v_add_f32_e32 v69, v69, v70
	v_lshl_add_u64 v[32:33], v[34:35], 3, s[34:35]
	ds_write_b32 v164, v69
	global_store_dwordx2 v[32:33], v[68:69], off
	s_branch .LBB0_633

; #define LAS __attribute__((address_space(3)))
; __device__ __forceinline__ s16x4 vtr(const LAS unsigned char* p) { return __builtin_bit_cast(s16x4, __builtin_amdgcn_ds_read_tr16_b64_v4i16((LAS s16x4*)p)); }
; template <bool MERGE> __device__ __forceinline__ void compute_b(LAS unsigned char* lds, const UD& x, unsigned char* ws, unsigned char* dout, int wid, int lane, const u32x4 (&pw)[10], float mx, float lsum) {
;     ...
;     f32x16 o[2]; o[0] = f32x16{}; o[1] = f32x16{};
;     const int vlane = ((lane >> 4) & 1) * 32 + (lane & 3) * 8 + (4 * hi + ((lane & 15) >> 2)) * 64;
; #pragma unroll
;     for (int g = 0; g < 10; ++g) {
;         const bf16x8 pa = __builtin_bit_cast(bf16x8, pw[g]);
; #pragma unroll
;         for (int d0 = 0; d0 < 2; ++d0) {
;             const LAS unsigned char* vp = lds + L_V + d0 * VDS + (sbase + 16 * g) * 64 + vlane;
;             const s16x4 lo = vtr(vp), hh = vtr(vp + 512);
;             const bf16x8 vf = (bf16x8){lo[0], lo[1], lo[2], lo[3], hh[0], hh[1], hh[2], hh[3]};
;             o[d0] = __builtin_amdgcn_mfma_f32_32x32x16_bf16(pa, vf, o[d0], 0, 0, 0);
;         }
;     }
;     LAS float* wsf = (LAS float*)(lds + L_WS + wid * 256);
;     LAS bf16_t* stg = (LAS bf16_t*)(lds + L_OST + wid * 4096);
;     if (hi == 0) {
;         wsf[r32] = lsum;
;         if (MERGE) wsf[32 + r32] = mx;
.LBB0_938:
	ds_read_b64_tr_b16 v[232:233], v152 offset:57472
	ds_read_b64_tr_b16 v[234:235], v152 offset:57984
	ds_read_b64_tr_b16 v[242:243], v153 offset:28736
	ds_read_b64_tr_b16 v[244:245], v153 offset:29248
	ds_read_b64_tr_b16 v[246:247], v152 offset:58496
	ds_read_b64_tr_b16 v[248:249], v152 offset:59008
	ds_read_b64_tr_b16 v[196:197], v153 offset:29760
	ds_read_b64_tr_b16 v[198:199], v153 offset:30272
	s_waitcnt lgkmcnt(6)
	v_mfma_f32_32x32x16_bf16 v[0:15], v[16:19], v[232:235], 0
	ds_read_b64_tr_b16 v[232:233], v152 offset:59520
	ds_read_b64_tr_b16 v[234:235], v152 offset:60032
	s_waitcnt lgkmcnt(6)
	v_mfma_f32_32x32x16_bf16 v[16:31], v[16:19], v[242:245], 0
	ds_read_b64_tr_b16 v[242:243], v153 offset:30784
	ds_read_b64_tr_b16 v[244:245], v153 offset:31296
	s_waitcnt lgkmcnt(6)
	v_mfma_f32_32x32x16_bf16 v[0:15], v[64:67], v[246:249], v[0:15]
	ds_read_b64_tr_b16 v[246:247], v152 offset:60544
	ds_read_b64_tr_b16 v[248:249], v152 offset:61056
	s_waitcnt lgkmcnt(6)
	v_mfma_f32_32x32x16_bf16 v[16:31], v[64:67], v[196:199], v[16:31]
	ds_read_b64_tr_b16 v[196:197], v153 offset:31808
	ds_read_b64_tr_b16 v[198:199], v153 offset:32320
	s_waitcnt lgkmcnt(6)
	v_mfma_f32_32x32x16_bf16 v[0:15], v[60:63], v[232:235], v[0:15]
	ds_read_b64_tr_b16 v[232:233], v152 offset:61568
	ds_read_b64_tr_b16 v[234:235], v152 offset:62080
	s_waitcnt lgkmcnt(6)
	v_mfma_f32_32x32x16_bf16 v[16:31], v[60:63], v[242:245], v[16:31]
	ds_read_b64_tr_b16 v[242:243], v153 offset:32832
	ds_read_b64_tr_b16 v[244:245], v153 offset:33344
	s_waitcnt lgkmcnt(6)
	v_mfma_f32_32x32x16_bf16 v[0:15], v[56:59], v[246:249], v[0:15]
	ds_read_b64_tr_b16 v[246:247], v152 offset:62592
	ds_read_b64_tr_b16 v[248:249], v152 offset:63104
	s_waitcnt lgkmcnt(6)
	v_mfma_f32_32x32x16_bf16 v[16:31], v[56:59], v[196:199], v[16:31]
	ds_read_b64_tr_b16 v[196:197], v153 offset:33856
	ds_read_b64_tr_b16 v[198:199], v153 offset:34368
	s_waitcnt lgkmcnt(6)
	v_mfma_f32_32x32x16_bf16 v[0:15], v[52:55], v[232:235], v[0:15]
	ds_read_b64_tr_b16 v[232:233], v152 offset:63616
	ds_read_b64_tr_b16 v[234:235], v152 offset:64128
	s_waitcnt lgkmcnt(6)
	v_mfma_f32_32x32x16_bf16 v[16:31], v[52:55], v[242:245], v[16:31]
	ds_read_b64_tr_b16 v[242:243], v153 offset:34880
	ds_read_b64_tr_b16 v[244:245], v153 offset:35392
	s_waitcnt lgkmcnt(6)
	v_mfma_f32_32x32x16_bf16 v[0:15], v[48:51], v[246:249], v[0:15]
	ds_read_b64_tr_b16 v[246:247], v152 offset:64640
	ds_read_b64_tr_b16 v[248:249], v152 offset:65152
	s_waitcnt lgkmcnt(6)
	v_mfma_f32_32x32x16_bf16 v[16:31], v[48:51], v[196:199], v[16:31]
	ds_read_b64_tr_b16 v[196:197], v153 offset:35904
	ds_read_b64_tr_b16 v[198:199], v153 offset:36416
	s_waitcnt lgkmcnt(6)
	v_mfma_f32_32x32x16_bf16 v[0:15], v[44:47], v[232:235], v[0:15]
	ds_read_b64_tr_b16 v[232:233], v153 offset:8192
	ds_read_b64_tr_b16 v[234:235], v153 offset:8704
	s_waitcnt lgkmcnt(6)
	v_mfma_f32_32x32x16_bf16 v[16:31], v[44:47], v[242:245], v[16:31]
	ds_read_b64_tr_b16 v[242:243], v153 offset:36928
	ds_read_b64_tr_b16 v[244:245], v153 offset:37440
	s_waitcnt lgkmcnt(6)
	v_mfma_f32_32x32x16_bf16 v[0:15], v[40:43], v[246:249], v[0:15]
	ds_read_b64_tr_b16 v[246:247], v153 offset:9216
	ds_read_b64_tr_b16 v[248:249], v153 offset:9728
	s_waitcnt lgkmcnt(6)
	v_mfma_f32_32x32x16_bf16 v[16:31], v[40:43], v[196:199], v[16:31]
	ds_read_b64_tr_b16 v[196:197], v153 offset:37952
	ds_read_b64_tr_b16 v[198:199], v153 offset:38464
	s_waitcnt lgkmcnt(6)
	v_mfma_f32_32x32x16_bf16 v[0:15], v[36:39], v[232:235], v[0:15]
	s_waitcnt lgkmcnt(4)
	v_mfma_f32_32x32x16_bf16 v[16:31], v[36:39], v[242:245], v[16:31]
	s_waitcnt lgkmcnt(2)
	v_mfma_f32_32x32x16_bf16 v[0:15], v[32:35], v[246:249], v[0:15]
	s_waitcnt lgkmcnt(0)
	v_mfma_f32_32x32x16_bf16 v[16:31], v[32:35], v[196:199], v[16:31]
	s_and_saveexec_b64 s[18:19], s[12:13]
	s_cbranch_execz .LBB0_940
	v_add_f32_e32 v32, v69, v70
	ds_write_b32 v160, v32
	ds_write_b32 v161, v68 offset:128
